# xor-shuffle reductions (lane^1,2,4,8) in residual epilogues and row-norm loops via DPP moves instead of ds_bpermute
# baseline (speedup 1.0000x reference)
.LBB0_45:
	v_or_b32_e32 v178, v211, v212
	v_or_b32_e32 v241, s18, v178
	v_lshl_add_u32 v178, v241, 8, v226
	ds_read_b128 v[248:251], v178
	s_waitcnt vmcnt(3) lgkmcnt(0)
	v_pk_add_f32 v[248:249], v[128:129], v[248:249]
	v_pk_add_f32 v[250:251], v[130:131], v[250:251]
	v_pk_mul_f32 v[178:179], v[248:249], v[248:249]
	v_pk_mul_f32 v[242:243], v[250:251], v[250:251]
	v_add_f32_e32 v178, v178, v179
	v_add_f32_e32 v190, v242, v243
	v_add_f32_e32 v178, v178, v190
	s_nop 1
	v_mov_b32_dpp v179, v178 quad_perm:[1,0,3,2] row_mask:0xf bank_mask:0xf
	s_waitcnt lgkmcnt(0)
	v_add_f32_e32 v190, v178, v179
	s_nop 1
	v_mov_b32_dpp v242, v190 quad_perm:[2,3,0,1] row_mask:0xf bank_mask:0xf
	v_add_u32_e32 v178, s27, v241
	v_ashrrev_i32_e32 v179, 31, v178
	s_waitcnt lgkmcnt(0)
	v_add_f32_e32 v190, v190, v242
	s_nop 1
	v_mov_b32_dpp v254, v190 row_half_mirror row_mask:0xf bank_mask:0xf
	v_lshlrev_b64 v[242:243], 10, v[178:179]
	v_lshl_add_u64 v[252:253], v[242:243], 0, v[168:169]
	v_lshl_add_u64 v[242:243], v[252:253], 2, s[4:5]
	global_store_dwordx4 v[242:243], v[248:251], off
	s_waitcnt lgkmcnt(0)
	v_add_f32_e32 v242, v190, v254
	s_nop 1
	v_mov_b32_dpp v243, v242 row_mirror row_mask:0xf bank_mask:0xf
	v_cvt_pk_bf16_f32 v248, v248, v249
	v_cvt_pk_bf16_f32 v249, v250, v251
	v_lshl_add_u64 v[250:251], v[252:253], 1, s[24:25]
	global_store_dwordx2 v[250:251], v[248:249], off
	s_and_saveexec_b64 s[18:19], s[6:7]
	s_cbranch_execz .LBB0_47
	v_lshlrev_b64 v[178:179], 6, v[178:179]
	s_waitcnt lgkmcnt(0)
	v_add_f32_e32 v190, v242, v243
	v_lshl_add_u64 v[178:179], s[14:15], 0, v[178:179]
	global_store_dword v[178:179], v190, off
.LBB0_47:
	s_or_b64 exec, exec, s[18:19]
	v_bitop3_b32 v179, v241, v180, 4 bitop3:0x36
	v_or_b32_e32 v190, 4, v241
	v_lshlrev_b32_e32 v179, 4, v179
	v_lshlrev_b32_e32 v178, 8, v190
	v_and_b32_e32 v179, 0xf0, v179
	v_add3_u32 v178, s22, v178, v179
	ds_read_b128 v[248:251], v178
	s_waitcnt vmcnt(4) lgkmcnt(0)
	v_pk_add_f32 v[248:249], v[132:133], v[248:249]
	v_pk_add_f32 v[250:251], v[134:135], v[250:251]
	v_pk_mul_f32 v[178:179], v[248:249], v[248:249]
	v_pk_mul_f32 v[242:243], v[250:251], v[250:251]
	v_add_f32_e32 v178, v178, v179
	v_add_f32_e32 v242, v242, v243
	v_add_f32_e32 v178, v178, v242
	s_nop 1
	v_mov_b32_dpp v179, v178 quad_perm:[1,0,3,2] row_mask:0xf bank_mask:0xf
	s_waitcnt lgkmcnt(0)
	v_add_f32_e32 v242, v178, v179
	s_nop 1
	v_mov_b32_dpp v243, v242 quad_perm:[2,3,0,1] row_mask:0xf bank_mask:0xf
	v_add_u32_e32 v178, s27, v190
	v_ashrrev_i32_e32 v179, 31, v178
	s_waitcnt lgkmcnt(0)
	v_add_f32_e32 v190, v242, v243
	s_nop 1
	v_mov_b32_dpp v254, v190 row_half_mirror row_mask:0xf bank_mask:0xf
	v_lshlrev_b64 v[242:243], 10, v[178:179]
	v_lshl_add_u64 v[252:253], v[242:243], 0, v[168:169]
	v_lshl_add_u64 v[242:243], v[252:253], 2, s[4:5]
	global_store_dwordx4 v[242:243], v[248:251], off
	s_waitcnt lgkmcnt(0)
	v_add_f32_e32 v242, v190, v254
	s_nop 1
	v_mov_b32_dpp v243, v242 row_mirror row_mask:0xf bank_mask:0xf
	v_cvt_pk_bf16_f32 v248, v248, v249
	v_cvt_pk_bf16_f32 v249, v250, v251
	v_lshl_add_u64 v[250:251], v[252:253], 1, s[24:25]
	global_store_dwordx2 v[250:251], v[248:249], off
	s_and_saveexec_b64 s[18:19], s[6:7]
	s_cbranch_execz .LBB0_49
	v_lshlrev_b64 v[178:179], 6, v[178:179]
	s_waitcnt lgkmcnt(0)
	v_add_f32_e32 v190, v242, v243
	v_lshl_add_u64 v[178:179], s[14:15], 0, v[178:179]
	global_store_dword v[178:179], v190, off
.LBB0_49:
	s_or_b64 exec, exec, s[18:19]
	v_bitop3_b32 v179, v241, v180, 8 bitop3:0x36
	v_or_b32_e32 v190, 8, v241
	v_lshlrev_b32_e32 v179, 4, v179
	v_lshlrev_b32_e32 v178, 8, v190
	v_and_b32_e32 v179, 0xf0, v179
	v_add3_u32 v178, s22, v178, v179
	ds_read_b128 v[248:251], v178
	s_waitcnt vmcnt(5) lgkmcnt(0)
	v_pk_add_f32 v[248:249], v[136:137], v[248:249]
	v_pk_add_f32 v[250:251], v[138:139], v[250:251]
	v_pk_mul_f32 v[178:179], v[248:249], v[248:249]
	v_pk_mul_f32 v[242:243], v[250:251], v[250:251]
	v_add_f32_e32 v178, v178, v179
	v_add_f32_e32 v242, v242, v243
	v_add_f32_e32 v178, v178, v242
	s_nop 1
	v_mov_b32_dpp v179, v178 quad_perm:[1,0,3,2] row_mask:0xf bank_mask:0xf
	s_waitcnt lgkmcnt(0)
	v_add_f32_e32 v242, v178, v179
	s_nop 1
	v_mov_b32_dpp v243, v242 quad_perm:[2,3,0,1] row_mask:0xf bank_mask:0xf
	v_add_u32_e32 v178, s27, v190
	v_ashrrev_i32_e32 v179, 31, v178
	s_waitcnt lgkmcnt(0)
	v_add_f32_e32 v190, v242, v243
	s_nop 1
	v_mov_b32_dpp v254, v190 row_half_mirror row_mask:0xf bank_mask:0xf
	v_lshlrev_b64 v[242:243], 10, v[178:179]
	v_lshl_add_u64 v[252:253], v[242:243], 0, v[168:169]
	v_lshl_add_u64 v[242:243], v[252:253], 2, s[4:5]
	global_store_dwordx4 v[242:243], v[248:251], off
	s_waitcnt lgkmcnt(0)
	v_add_f32_e32 v242, v190, v254
	s_nop 1
	v_mov_b32_dpp v243, v242 row_mirror row_mask:0xf bank_mask:0xf
	v_cvt_pk_bf16_f32 v248, v248, v249
	v_cvt_pk_bf16_f32 v249, v250, v251
	v_lshl_add_u64 v[250:251], v[252:253], 1, s[24:25]
	global_store_dwordx2 v[250:251], v[248:249], off
	s_and_saveexec_b64 s[18:19], s[6:7]
	s_cbranch_execz .LBB0_51
	v_lshlrev_b64 v[178:179], 6, v[178:179]
	s_waitcnt lgkmcnt(0)
	v_add_f32_e32 v190, v242, v243
	v_lshl_add_u64 v[178:179], s[14:15], 0, v[178:179]
	global_store_dword v[178:179], v190, off
.LBB0_51:
	s_or_b64 exec, exec, s[18:19]
	v_bitop3_b32 v179, v241, v180, 12 bitop3:0x36
	v_or_b32_e32 v190, 12, v241
	v_lshlrev_b32_e32 v179, 4, v179
	v_lshlrev_b32_e32 v178, 8, v190
	v_and_b32_e32 v179, 0xf0, v179
	v_add3_u32 v178, s22, v178, v179
	ds_read_b128 v[248:251], v178
	s_waitcnt vmcnt(6) lgkmcnt(0)
	v_pk_add_f32 v[248:249], v[140:141], v[248:249]
	v_pk_add_f32 v[250:251], v[142:143], v[250:251]
	v_pk_mul_f32 v[178:179], v[248:249], v[248:249]
	v_pk_mul_f32 v[242:243], v[250:251], v[250:251]
	v_add_f32_e32 v178, v178, v179
	v_add_f32_e32 v241, v242, v243
	v_add_f32_e32 v178, v178, v241
	s_nop 1
	v_mov_b32_dpp v179, v178 quad_perm:[1,0,3,2] row_mask:0xf bank_mask:0xf
	s_waitcnt lgkmcnt(0)
	v_add_f32_e32 v241, v178, v179
	s_nop 1
	v_mov_b32_dpp v242, v241 quad_perm:[2,3,0,1] row_mask:0xf bank_mask:0xf
	v_add_u32_e32 v178, s27, v190
	v_ashrrev_i32_e32 v179, 31, v178
	s_waitcnt lgkmcnt(0)
	v_add_f32_e32 v190, v241, v242
	s_nop 1
	v_mov_b32_dpp v241, v190 row_half_mirror row_mask:0xf bank_mask:0xf
	v_lshlrev_b64 v[242:243], 10, v[178:179]
	v_lshl_add_u64 v[252:253], v[242:243], 0, v[168:169]
	v_lshl_add_u64 v[242:243], v[252:253], 2, s[4:5]
	global_store_dwordx4 v[242:243], v[248:251], off
	s_waitcnt lgkmcnt(0)
	v_add_f32_e32 v241, v190, v241
	s_nop 1
	v_mov_b32_dpp v242, v241 row_mirror row_mask:0xf bank_mask:0xf
	v_cvt_pk_bf16_f32 v248, v248, v249
	v_cvt_pk_bf16_f32 v249, v250, v251
	v_lshl_add_u64 v[250:251], v[252:253], 1, s[24:25]
	global_store_dwordx2 v[250:251], v[248:249], off
	s_and_saveexec_b64 s[18:19], s[6:7]
	s_cbranch_execz .LBB0_42
	v_lshlrev_b64 v[178:179], 6, v[178:179]
	s_waitcnt lgkmcnt(0)
	v_add_f32_e32 v190, v241, v242
	v_lshl_add_u64 v[178:179], s[14:15], 0, v[178:179]
	global_store_dword v[178:179], v190, off
	s_branch .LBB0_42

.LBB0_728:
	v_or_b32_e32 v178, v211, v212
	v_or_b32_e32 v241, s16, v178
	v_lshl_add_u32 v178, v241, 8, v226
	ds_read_b128 v[248:251], v178
	s_waitcnt vmcnt(3) lgkmcnt(0)
	v_pk_add_f32 v[248:249], v[128:129], v[248:249]
	v_pk_add_f32 v[250:251], v[130:131], v[250:251]
	v_pk_mul_f32 v[178:179], v[248:249], v[248:249]
	v_pk_mul_f32 v[242:243], v[250:251], v[250:251]
	v_add_f32_e32 v178, v178, v179
	v_add_f32_e32 v190, v242, v243
	v_add_f32_e32 v178, v178, v190
	s_nop 1
	v_mov_b32_dpp v179, v178 quad_perm:[1,0,3,2] row_mask:0xf bank_mask:0xf
	s_waitcnt lgkmcnt(0)
	v_add_f32_e32 v190, v178, v179
	s_nop 1
	v_mov_b32_dpp v242, v190 quad_perm:[2,3,0,1] row_mask:0xf bank_mask:0xf
	v_add_u32_e32 v178, s22, v241
	v_ashrrev_i32_e32 v179, 31, v178
	s_waitcnt lgkmcnt(0)
	v_add_f32_e32 v190, v190, v242
	s_nop 1
	v_mov_b32_dpp v254, v190 row_half_mirror row_mask:0xf bank_mask:0xf
	v_lshlrev_b64 v[242:243], 10, v[178:179]
	v_lshl_add_u64 v[252:253], v[242:243], 0, v[168:169]
	v_lshl_add_u64 v[242:243], v[252:253], 2, s[4:5]
	global_store_dwordx4 v[242:243], v[248:251], off
	s_waitcnt lgkmcnt(0)
	v_add_f32_e32 v242, v190, v254
	s_nop 1
	v_mov_b32_dpp v243, v242 row_mirror row_mask:0xf bank_mask:0xf
	v_cvt_pk_bf16_f32 v248, v248, v249
	v_cvt_pk_bf16_f32 v249, v250, v251
	v_lshl_add_u64 v[250:251], v[252:253], 1, s[24:25]
	global_store_dwordx2 v[250:251], v[248:249], off
	s_and_saveexec_b64 s[16:17], s[6:7]
	s_cbranch_execz .LBB0_730
	v_lshlrev_b64 v[178:179], 6, v[178:179]
	s_waitcnt lgkmcnt(0)
	v_add_f32_e32 v190, v242, v243
	v_lshl_add_u64 v[178:179], s[12:13], 0, v[178:179]
	global_store_dword v[178:179], v190, off
.LBB0_730:
	s_or_b64 exec, exec, s[16:17]
	v_bitop3_b32 v179, v241, v180, 4 bitop3:0x36
	v_or_b32_e32 v190, 4, v241
	v_lshlrev_b32_e32 v179, 4, v179
	v_lshlrev_b32_e32 v178, 8, v190
	v_and_b32_e32 v179, 0xf0, v179
	v_add3_u32 v178, s20, v178, v179
	ds_read_b128 v[248:251], v178
	s_waitcnt vmcnt(4) lgkmcnt(0)
	v_pk_add_f32 v[248:249], v[132:133], v[248:249]
	v_pk_add_f32 v[250:251], v[134:135], v[250:251]
	v_pk_mul_f32 v[178:179], v[248:249], v[248:249]
	v_pk_mul_f32 v[242:243], v[250:251], v[250:251]
	v_add_f32_e32 v178, v178, v179
	v_add_f32_e32 v242, v242, v243
	v_add_f32_e32 v178, v178, v242
	s_nop 1
	v_mov_b32_dpp v179, v178 quad_perm:[1,0,3,2] row_mask:0xf bank_mask:0xf
	s_waitcnt lgkmcnt(0)
	v_add_f32_e32 v242, v178, v179
	s_nop 1
	v_mov_b32_dpp v243, v242 quad_perm:[2,3,0,1] row_mask:0xf bank_mask:0xf
	v_add_u32_e32 v178, s22, v190
	v_ashrrev_i32_e32 v179, 31, v178
	s_waitcnt lgkmcnt(0)
	v_add_f32_e32 v190, v242, v243
	s_nop 1
	v_mov_b32_dpp v254, v190 row_half_mirror row_mask:0xf bank_mask:0xf
	v_lshlrev_b64 v[242:243], 10, v[178:179]
	v_lshl_add_u64 v[252:253], v[242:243], 0, v[168:169]
	v_lshl_add_u64 v[242:243], v[252:253], 2, s[4:5]
	global_store_dwordx4 v[242:243], v[248:251], off
	s_waitcnt lgkmcnt(0)
	v_add_f32_e32 v242, v190, v254
	s_nop 1
	v_mov_b32_dpp v243, v242 row_mirror row_mask:0xf bank_mask:0xf
	v_cvt_pk_bf16_f32 v248, v248, v249
	v_cvt_pk_bf16_f32 v249, v250, v251
	v_lshl_add_u64 v[250:251], v[252:253], 1, s[24:25]
	global_store_dwordx2 v[250:251], v[248:249], off
	s_and_saveexec_b64 s[16:17], s[6:7]
	s_cbranch_execz .LBB0_732
	v_lshlrev_b64 v[178:179], 6, v[178:179]
	s_waitcnt lgkmcnt(0)
	v_add_f32_e32 v190, v242, v243
	v_lshl_add_u64 v[178:179], s[12:13], 0, v[178:179]
	global_store_dword v[178:179], v190, off
.LBB0_732:
	s_or_b64 exec, exec, s[16:17]
	v_bitop3_b32 v179, v241, v180, 8 bitop3:0x36
	v_or_b32_e32 v190, 8, v241
	v_lshlrev_b32_e32 v179, 4, v179
	v_lshlrev_b32_e32 v178, 8, v190
	v_and_b32_e32 v179, 0xf0, v179
	v_add3_u32 v178, s20, v178, v179
	ds_read_b128 v[248:251], v178
	s_waitcnt vmcnt(5) lgkmcnt(0)
	v_pk_add_f32 v[248:249], v[136:137], v[248:249]
	v_pk_add_f32 v[250:251], v[138:139], v[250:251]
	v_pk_mul_f32 v[178:179], v[248:249], v[248:249]
	v_pk_mul_f32 v[242:243], v[250:251], v[250:251]
	v_add_f32_e32 v178, v178, v179
	v_add_f32_e32 v242, v242, v243
	v_add_f32_e32 v178, v178, v242
	s_nop 1
	v_mov_b32_dpp v179, v178 quad_perm:[1,0,3,2] row_mask:0xf bank_mask:0xf
	s_waitcnt lgkmcnt(0)
	v_add_f32_e32 v242, v178, v179
	s_nop 1
	v_mov_b32_dpp v243, v242 quad_perm:[2,3,0,1] row_mask:0xf bank_mask:0xf
	v_add_u32_e32 v178, s22, v190
	v_ashrrev_i32_e32 v179, 31, v178
	s_waitcnt lgkmcnt(0)
	v_add_f32_e32 v190, v242, v243
	s_nop 1
	v_mov_b32_dpp v254, v190 row_half_mirror row_mask:0xf bank_mask:0xf
	v_lshlrev_b64 v[242:243], 10, v[178:179]
	v_lshl_add_u64 v[252:253], v[242:243], 0, v[168:169]
	v_lshl_add_u64 v[242:243], v[252:253], 2, s[4:5]
	global_store_dwordx4 v[242:243], v[248:251], off
	s_waitcnt lgkmcnt(0)
	v_add_f32_e32 v242, v190, v254
	s_nop 1
	v_mov_b32_dpp v243, v242 row_mirror row_mask:0xf bank_mask:0xf
	v_cvt_pk_bf16_f32 v248, v248, v249
	v_cvt_pk_bf16_f32 v249, v250, v251
	v_lshl_add_u64 v[250:251], v[252:253], 1, s[24:25]
	global_store_dwordx2 v[250:251], v[248:249], off
	s_and_saveexec_b64 s[16:17], s[6:7]
	s_cbranch_execz .LBB0_734
	v_lshlrev_b64 v[178:179], 6, v[178:179]
	s_waitcnt lgkmcnt(0)
	v_add_f32_e32 v190, v242, v243
	v_lshl_add_u64 v[178:179], s[12:13], 0, v[178:179]
	global_store_dword v[178:179], v190, off
.LBB0_734:
	s_or_b64 exec, exec, s[16:17]
	v_bitop3_b32 v179, v241, v180, 12 bitop3:0x36
	v_or_b32_e32 v190, 12, v241
	v_lshlrev_b32_e32 v179, 4, v179
	v_lshlrev_b32_e32 v178, 8, v190
	v_and_b32_e32 v179, 0xf0, v179
	v_add3_u32 v178, s20, v178, v179
	ds_read_b128 v[248:251], v178
	s_waitcnt vmcnt(6) lgkmcnt(0)
	v_pk_add_f32 v[248:249], v[140:141], v[248:249]
	v_pk_add_f32 v[250:251], v[142:143], v[250:251]
	v_pk_mul_f32 v[178:179], v[248:249], v[248:249]
	v_pk_mul_f32 v[242:243], v[250:251], v[250:251]
	v_add_f32_e32 v178, v178, v179
	v_add_f32_e32 v241, v242, v243
	v_add_f32_e32 v178, v178, v241
	s_nop 1
	v_mov_b32_dpp v179, v178 quad_perm:[1,0,3,2] row_mask:0xf bank_mask:0xf
	s_waitcnt lgkmcnt(0)
	v_add_f32_e32 v241, v178, v179
	s_nop 1
	v_mov_b32_dpp v242, v241 quad_perm:[2,3,0,1] row_mask:0xf bank_mask:0xf
	v_add_u32_e32 v178, s22, v190
	v_ashrrev_i32_e32 v179, 31, v178
	s_waitcnt lgkmcnt(0)
	v_add_f32_e32 v190, v241, v242
	s_nop 1
	v_mov_b32_dpp v241, v190 row_half_mirror row_mask:0xf bank_mask:0xf
	v_lshlrev_b64 v[242:243], 10, v[178:179]
	v_lshl_add_u64 v[252:253], v[242:243], 0, v[168:169]
	v_lshl_add_u64 v[242:243], v[252:253], 2, s[4:5]
	global_store_dwordx4 v[242:243], v[248:251], off
	s_waitcnt lgkmcnt(0)
	v_add_f32_e32 v241, v190, v241
	s_nop 1
	v_mov_b32_dpp v242, v241 row_mirror row_mask:0xf bank_mask:0xf
	v_cvt_pk_bf16_f32 v248, v248, v249
	v_cvt_pk_bf16_f32 v249, v250, v251
	v_lshl_add_u64 v[250:251], v[252:253], 1, s[24:25]
	global_store_dwordx2 v[250:251], v[248:249], off
	s_and_saveexec_b64 s[16:17], s[6:7]
	s_cbranch_execz .LBB0_725
	v_lshlrev_b64 v[178:179], 6, v[178:179]
	s_waitcnt lgkmcnt(0)
	v_add_f32_e32 v190, v241, v242
	v_lshl_add_u64 v[178:179], s[12:13], 0, v[178:179]
	global_store_dword v[178:179], v190, off
	s_branch .LBB0_725

.LBB0_789:
	v_or_b32_e32 v178, v211, v212
	v_or_b32_e32 v241, s16, v178
	v_lshl_add_u32 v178, v241, 8, v226
	ds_read_b128 v[248:251], v178
	s_waitcnt vmcnt(3) lgkmcnt(0)
	v_pk_add_f32 v[248:249], v[128:129], v[248:249]
	v_pk_add_f32 v[250:251], v[130:131], v[250:251]
	v_pk_mul_f32 v[178:179], v[248:249], v[248:249]
	v_pk_mul_f32 v[242:243], v[250:251], v[250:251]
	v_add_f32_e32 v178, v178, v179
	v_add_f32_e32 v242, v242, v243
	v_add_f32_e32 v178, v178, v242
	s_nop 1
	v_mov_b32_dpp v179, v178 quad_perm:[1,0,3,2] row_mask:0xf bank_mask:0xf
	s_waitcnt lgkmcnt(0)
	v_add_f32_e32 v242, v178, v179
	s_nop 1
	v_mov_b32_dpp v243, v242 quad_perm:[2,3,0,1] row_mask:0xf bank_mask:0xf
	v_add_u32_e32 v178, s22, v241
	v_ashrrev_i32_e32 v179, 31, v178
	s_waitcnt lgkmcnt(0)
	v_add_f32_e32 v254, v242, v243
	s_nop 1
	v_mov_b32_dpp v190, v254 row_half_mirror row_mask:0xf bank_mask:0xf
	v_lshlrev_b64 v[242:243], 10, v[178:179]
	v_lshl_add_u64 v[252:253], v[242:243], 0, v[168:169]
	v_lshl_add_u64 v[242:243], v[252:253], 2, s[4:5]
	global_store_dwordx4 v[242:243], v[248:251], off
	s_waitcnt lgkmcnt(0)
	v_add_f32_e32 v242, v254, v190
	s_nop 1
	v_mov_b32_dpp v243, v242 row_mirror row_mask:0xf bank_mask:0xf
	v_cvt_pk_bf16_f32 v248, v248, v249
	v_cvt_pk_bf16_f32 v249, v250, v251
	v_lshl_add_u64 v[250:251], v[252:253], 1, s[24:25]
	global_store_dwordx2 v[250:251], v[248:249], off
	s_and_saveexec_b64 s[16:17], s[6:7]
	s_cbranch_execz .LBB0_791
	v_lshlrev_b64 v[178:179], 6, v[178:179]
	s_waitcnt lgkmcnt(0)
	v_add_f32_e32 v190, v242, v243
	v_lshl_add_u64 v[178:179], s[12:13], 0, v[178:179]
	global_store_dword v[178:179], v190, off

.LBB0_806:
	v_mov_b32_e32 v0, v185
	v_mov_b32_e32 v7, v169
	v_and_b32_e32 v1, 63, v0
	v_ashrrev_i32_e32 v0, 4, v0
	v_and_b32_e32 v0, -4, v0
	v_add_u32_e32 v14, s27, v0
	v_lshlrev_b32_e32 v6, 4, v1
	v_ashrrev_i32_e32 v15, 31, v14
	v_lshl_add_u64 v[12:13], s[6:7], 0, v[6:7]
	v_lshlrev_b64 v[2:3], 10, v[14:15]
	v_lshl_add_u64 v[2:3], v[12:13], 0, v[2:3]
	global_load_dwordx4 v[16:19], v[2:3], off
	v_cmp_lt_i32_e32 vcc, v194, v193
	v_lshlrev_b32_e32 v168, 3, v1
	v_lshrrev_b32_e32 v0, 7, v14
	v_ashrrev_i32_e32 v1, 7, v14
	s_movk_i32 s0, 0xffc0
	v_bfi_b32 v0, s0, v1, v0
	v_ashrrev_i32_e32 v1, 31, v0
	v_lshlrev_b64 v[0:1], 10, v[0:1]
	v_lshl_add_u64 v[0:1], s[12:13], 0, v[0:1]
	v_lshl_add_u64 v[4:5], v[0:1], 0, v[6:7]
	v_lshlrev_b64 v[0:1], 11, v[14:15]
	v_lshl_add_u64 v[10:11], s[8:9], 0, v[168:169]
	v_lshl_add_u64 v[8:9], s[10:11], 0, v[168:169]
	s_waitcnt vmcnt(0)
	v_and_b32_e32 v21, 0xffff0000, v16
	v_lshlrev_b32_e32 v20, 16, v16
	v_mul_f32_e32 v24, v21, v21
	v_lshlrev_b32_e32 v22, 16, v17
	v_fmac_f32_e32 v24, v20, v20
	v_and_b32_e32 v23, 0xffff0000, v17
	v_fmac_f32_e32 v24, v22, v22
	v_and_b32_e32 v2, 0xffff0000, v18
	v_lshlrev_b32_e32 v3, 16, v18
	v_fmac_f32_e32 v24, v23, v23
	v_pk_mul_f32 v[16:17], v[2:3], v[2:3]
	s_nop 0
	v_add_f32_e32 v17, v17, v24
	v_add_f32_e32 v24, v16, v17
	v_and_b32_e32 v16, 0xffff0000, v19
	v_lshlrev_b32_e32 v17, 16, v19
	v_pk_mul_f32 v[18:19], v[16:17], v[16:17]
	s_nop 0
	v_add_f32_e32 v19, v19, v24
	v_add_f32_e32 v18, v18, v19
	v_cndmask_b32_e32 v19, v191, v194, vcc
	v_lshlrev_b32_e32 v28, 2, v19
	s_nop 1
	v_mov_b32_dpp v19, v18 quad_perm:[1,0,3,2] row_mask:0xf bank_mask:0xf
	v_cmp_lt_i32_e32 vcc, v195, v193
	s_waitcnt lgkmcnt(0)
	v_add_f32_e32 v18, v18, v19
	v_cndmask_b32_e32 v19, v191, v195, vcc
	v_lshlrev_b32_e32 v29, 2, v19
	s_nop 1
	v_mov_b32_dpp v19, v18 quad_perm:[2,3,0,1] row_mask:0xf bank_mask:0xf
	v_cmp_lt_i32_e32 vcc, v196, v193
	s_waitcnt lgkmcnt(0)
	v_add_f32_e32 v18, v18, v19
	v_cndmask_b32_e32 v19, v191, v196, vcc
	v_lshlrev_b32_e32 v30, 2, v19
	s_nop 1
	v_mov_b32_dpp v19, v18 row_half_mirror row_mask:0xf bank_mask:0xf
	v_cmp_lt_i32_e32 vcc, v197, v193
	s_waitcnt lgkmcnt(0)
	v_add_f32_e32 v18, v18, v19
	v_cndmask_b32_e32 v19, v191, v197, vcc
	v_lshlrev_b32_e32 v31, 2, v19
	s_nop 1
	v_mov_b32_dpp v19, v18 row_mirror row_mask:0xf bank_mask:0xf
	v_cmp_lt_i32_e32 vcc, v198, v193
	s_waitcnt lgkmcnt(0)
	v_add_f32_e32 v18, v18, v19
	v_cndmask_b32_e32 v19, v191, v198, vcc
	v_lshlrev_b32_e32 v32, 2, v19
	ds_bpermute_b32 v19, v32, v18
	v_cmp_lt_i32_e32 vcc, v199, v193
	s_waitcnt lgkmcnt(0)
	v_add_f32_e32 v18, v18, v19
	v_cndmask_b32_e32 v19, v191, v199, vcc
	v_lshlrev_b32_e32 v33, 2, v19
	ds_bpermute_b32 v19, v33, v18
	s_waitcnt lgkmcnt(0)
	v_add_f32_e32 v24, v18, v19
	v_lshl_add_u64 v[18:19], s[4:5], 0, v[0:1]
	v_fmamk_f32 v0, v24, 0x3b000000, v187
	v_cmp_gt_f32_e32 vcc, s28, v0
	v_mul_f32_e32 v1, 0x4b800000, v0
	s_nop 0
	v_cndmask_b32_e32 v0, v0, v1, vcc
	v_rsq_f32_e32 v0, v0
	s_nop 0
	v_mul_f32_e32 v1, 0x45800000, v0
	v_cndmask_b32_e32 v24, v0, v1, vcc
	v_mul_f32_e32 v0, v24, v20
	v_mul_f32_e32 v1, v24, v21
	v_mul_f32_e32 v3, v24, v3
	v_mul_f32_e32 v2, v24, v2
	v_cvt_pk_bf16_f32 v0, v0, v1
	v_mul_f32_e32 v1, v24, v22
	v_mul_f32_e32 v20, v24, v23
	v_cvt_pk_bf16_f32 v2, v3, v2
	v_mul_f32_e32 v3, v24, v17
	v_mul_f32_e32 v16, v24, v16
	v_cvt_pk_bf16_f32 v1, v1, v20
	v_cvt_pk_bf16_f32 v3, v3, v16
	v_lshl_add_u64 v[16:17], v[18:19], 0, v[6:7]
	global_store_dwordx4 v[16:17], v[0:3], off
	v_mov_b64_e32 v[16:17], s[82:83]
	s_nop 0
	v_lshlrev_b64 v[0:1], 9, v[14:15]
	v_lshl_add_u64 v[2:3], v[10:11], 0, v[0:1]
	v_lshl_add_u64 v[0:1], v[8:9], 0, v[0:1]
	global_load_dwordx2 v[24:25], v[2:3], off
	global_load_dwordx2 v[22:23], v[0:1], off
	v_mad_i64_i32 v[0:1], s[0:1], v14, s93, v[16:17]
	v_lshl_add_u64 v[0:1], v[0:1], 0, v[168:169]
	v_add_co_u32_e32 v0, vcc, s29, v0
	s_waitcnt vmcnt(1)
	v_lshlrev_b32_e32 v20, 16, v25
	v_addc_co_u32_e32 v1, vcc, 0, v1, vcc
	global_load_dwordx2 v[26:27], v[0:1], off offset:3072
	s_nop 0
	global_load_dwordx4 v[0:3], v[4:5], off
	s_waitcnt vmcnt(2)
	v_lshlrev_b32_e32 v34, 16, v23
	v_and_b32_e32 v35, 0xffff0000, v23
	v_and_b32_e32 v21, 0xffff0000, v25
	s_waitcnt vmcnt(1)
	v_lshlrev_b32_e32 v36, 16, v27
	v_mul_f32_e32 v15, 0x3d372713, v36
	v_mul_f32_e32 v15, v15, v36
	v_mov_b32_e32 v23, v36
	v_fmac_f32_e32 v23, v15, v23
	v_mul_f32_e32 v15, 0x3f4c422a, v23
	v_add_f32_e32 v15, v15, v15
	v_and_b32_e32 v37, 0xffff0000, v27
	v_mul_f32_e32 v15, 0x3fb8aa3b, v15
	v_exp_f32_e32 v38, v15
	v_mul_f32_e32 v15, 0x3d372713, v37
	s_waitcnt vmcnt(0)
	v_pk_fma_f32 v[2:3], v[2:3], v[34:35], v[20:21]
	v_mul_f32_e32 v15, v15, v37
	v_mov_b32_e32 v20, v37
	v_fmac_f32_e32 v20, v15, v20
	v_mul_f32_e32 v15, 0x3f4c422a, v20
	v_add_f32_e32 v15, v15, v15
	v_mul_f32_e32 v15, 0x3fb8aa3b, v15
	v_exp_f32_e32 v39, v15
	s_nop 0
	v_pk_add_f32 v[20:21], v[38:39], 1.0 op_sel_hi:[1,0]
	s_nop 0
	v_div_scale_f32 v15, s[0:1], v21, v21, 2.0
	v_rcp_f32_e32 v23, v15
	s_nop 0
	v_fma_f32 v25, -v15, v23, 1.0
	v_fmac_f32_e32 v23, v25, v23
	v_div_scale_f32 v25, vcc, 2.0, v21, 2.0
	v_mul_f32_e32 v27, v25, v23
	v_fma_f32 v34, -v15, v27, v25
	v_fmac_f32_e32 v27, v34, v23
	v_fma_f32 v15, -v15, v27, v25
	v_div_fmas_f32 v15, v15, v23, v27
	v_div_fixup_f32 v21, v15, v21, 2.0
	v_div_scale_f32 v15, s[0:1], v20, v20, 2.0
	v_rcp_f32_e32 v23, v15
	s_nop 0
	v_fma_f32 v25, -v15, v23, 1.0
	v_fmac_f32_e32 v23, v25, v23
	v_div_scale_f32 v25, vcc, 2.0, v20, 2.0
	v_mul_f32_e32 v27, v25, v23
	v_fma_f32 v34, -v15, v27, v25
	v_fmac_f32_e32 v27, v34, v23
	v_fma_f32 v15, -v15, v27, v25
	v_div_fmas_f32 v15, v15, v23, v27
	v_div_fixup_f32 v20, v15, v20, 2.0
	v_pk_add_f32 v[20:21], v[20:21], 1.0 op_sel_hi:[1,0] neg_lo:[1,0] neg_hi:[1,0]
	v_pk_mul_f32 v[34:35], v[36:37], 0.5 op_sel_hi:[1,0]
	v_pk_add_f32 v[20:21], v[20:21], 1.0 op_sel_hi:[1,0]
	v_lshlrev_b32_e32 v36, 16, v22
	v_pk_mul_f32 v[20:21], v[34:35], v[20:21]
	v_lshlrev_b32_e32 v34, 16, v24
	v_and_b32_e32 v35, 0xffff0000, v24
	v_lshlrev_b32_e32 v24, 16, v26
	v_mul_f32_e32 v15, 0x3d372713, v24
	v_and_b32_e32 v37, 0xffff0000, v22
	v_mul_f32_e32 v15, v15, v24
	v_mov_b32_e32 v22, v24
	v_fmac_f32_e32 v22, v15, v22
	v_mul_f32_e32 v15, 0x3f4c422a, v22
	v_add_f32_e32 v15, v15, v15
	v_and_b32_e32 v25, 0xffff0000, v26
	v_mul_f32_e32 v15, 0x3fb8aa3b, v15
	v_exp_f32_e32 v22, v15
	v_mul_f32_e32 v15, 0x3d372713, v25
	v_mul_f32_e32 v15, v15, v25
	v_mov_b32_e32 v23, v25
	v_fmac_f32_e32 v23, v15, v23
	v_mul_f32_e32 v15, 0x3f4c422a, v23
	v_add_f32_e32 v15, v15, v15
	v_mul_f32_e32 v15, 0x3fb8aa3b, v15
	v_exp_f32_e32 v23, v15
	v_pk_fma_f32 v[0:1], v[0:1], v[36:37], v[34:35]
	v_pk_mul_f32 v[24:25], v[24:25], 0.5 op_sel_hi:[1,0]
	v_pk_mul_f32 v[2:3], v[2:3], v[20:21]
	v_pk_add_f32 v[22:23], v[22:23], 1.0 op_sel_hi:[1,0]
	v_pk_mul_f32 v[20:21], v[2:3], v[2:3]
	v_div_scale_f32 v15, s[0:1], v23, v23, 2.0
	v_rcp_f32_e32 v26, v15
	s_nop 0
	v_fma_f32 v27, -v15, v26, 1.0
	v_fmac_f32_e32 v26, v27, v26
	v_div_scale_f32 v27, vcc, 2.0, v23, 2.0
	v_mul_f32_e32 v34, v27, v26
	v_fma_f32 v35, -v15, v34, v27
	v_fmac_f32_e32 v34, v35, v26
	v_fma_f32 v15, -v15, v34, v27
	v_div_fmas_f32 v15, v15, v26, v34
	v_div_fixup_f32 v23, v15, v23, 2.0
	v_div_scale_f32 v15, s[0:1], v22, v22, 2.0
	v_rcp_f32_e32 v26, v15
	s_nop 0
	v_fma_f32 v27, -v15, v26, 1.0
	v_fmac_f32_e32 v26, v27, v26
	v_div_scale_f32 v27, vcc, 2.0, v22, 2.0
	v_mul_f32_e32 v34, v27, v26
	v_fma_f32 v35, -v15, v34, v27
	v_fmac_f32_e32 v34, v35, v26
	v_fma_f32 v15, -v15, v34, v27
	v_div_fmas_f32 v15, v15, v26, v34
	v_div_fixup_f32 v22, v15, v22, 2.0
	v_pk_add_f32 v[22:23], v[22:23], 1.0 op_sel_hi:[1,0] neg_lo:[1,0] neg_hi:[1,0]
	s_nop 0
	v_pk_add_f32 v[22:23], v[22:23], 1.0 op_sel_hi:[1,0]
	s_nop 0
	v_pk_mul_f32 v[22:23], v[24:25], v[22:23]
	s_nop 0
	v_pk_mul_f32 v[0:1], v[0:1], v[22:23]
	s_nop 0
	v_pk_mul_f32 v[22:23], v[0:1], v[0:1]
	s_nop 0
	v_add_f32_e32 v15, v22, v23
	v_add_f32_e32 v15, v20, v15
	v_add_f32_e32 v15, v21, v15
	s_nop 1
	v_mov_b32_dpp v20, v15 quad_perm:[1,0,3,2] row_mask:0xf bank_mask:0xf
	s_waitcnt lgkmcnt(0)
	v_add_f32_e32 v15, v15, v20
	s_nop 1
	v_mov_b32_dpp v20, v15 quad_perm:[2,3,0,1] row_mask:0xf bank_mask:0xf
	s_waitcnt lgkmcnt(0)
	v_add_f32_e32 v15, v15, v20
	s_nop 1
	v_mov_b32_dpp v20, v15 row_half_mirror row_mask:0xf bank_mask:0xf
	s_waitcnt lgkmcnt(0)
	v_add_f32_e32 v15, v15, v20
	s_nop 1
	v_mov_b32_dpp v20, v15 row_mirror row_mask:0xf bank_mask:0xf
	s_waitcnt lgkmcnt(0)
	v_add_f32_e32 v15, v15, v20
	ds_bpermute_b32 v20, v32, v15
	s_waitcnt lgkmcnt(0)
	v_add_f32_e32 v15, v15, v20
	ds_bpermute_b32 v20, v33, v15
	s_waitcnt lgkmcnt(0)
	v_add_f32_e32 v15, v15, v20
	v_fmamk_f32 v15, v15, 0x3b800000, v187
	v_cmp_gt_f32_e32 vcc, s28, v15
	v_mul_f32_e32 v20, 0x4b800000, v15
	s_nop 0
	v_cndmask_b32_e32 v15, v15, v20, vcc
	v_rsq_f32_e32 v15, v15
	s_nop 0
	v_mul_f32_e32 v20, 0x45800000, v15
	v_cndmask_b32_e32 v20, v15, v20, vcc
	v_pk_mul_f32 v[0:1], v[0:1], v[20:21] op_sel_hi:[1,0]
	v_pk_mul_f32 v[2:3], v[2:3], v[20:21] op_sel_hi:[1,0]
	v_cvt_pk_bf16_f32 v0, v0, v1
	v_cvt_pk_bf16_f32 v1, v2, v3
	v_lshl_add_u64 v[2:3], v[18:19], 0, v[168:169]
	global_store_dwordx2 v[2:3], v[0:1], off offset:1536
	v_add_u32_e32 v0, 1, v14
	v_ashrrev_i32_e32 v1, 31, v0
	v_lshlrev_b64 v[18:19], 10, v[0:1]
	v_lshl_add_u64 v[18:19], v[12:13], 0, v[18:19]
	global_load_dwordx4 v[18:21], v[18:19], off
	v_lshlrev_b64 v[2:3], 11, v[0:1]
	s_waitcnt vmcnt(0)
	v_and_b32_e32 v26, 0xffff0000, v18
	v_lshlrev_b32_e32 v15, 16, v18
	v_mul_f32_e32 v24, v26, v26
	v_lshlrev_b32_e32 v27, 16, v19
	v_fmac_f32_e32 v24, v15, v15
	v_and_b32_e32 v34, 0xffff0000, v19
	v_fmac_f32_e32 v24, v27, v27
	v_and_b32_e32 v22, 0xffff0000, v20
	v_lshlrev_b32_e32 v23, 16, v20
	v_fmac_f32_e32 v24, v34, v34
	v_pk_mul_f32 v[18:19], v[22:23], v[22:23]
	v_lshlrev_b32_e32 v25, 16, v21
	v_add_f32_e32 v19, v19, v24
	v_and_b32_e32 v24, 0xffff0000, v21
	v_add_f32_e32 v20, v18, v19
	v_pk_mul_f32 v[18:19], v[24:25], v[24:25]
	s_nop 0
	v_add_f32_e32 v19, v19, v20
	v_add_f32_e32 v18, v18, v19
	s_nop 1
	v_mov_b32_dpp v19, v18 quad_perm:[1,0,3,2] row_mask:0xf bank_mask:0xf
	s_waitcnt lgkmcnt(0)
	v_add_f32_e32 v18, v18, v19
	s_nop 1
	v_mov_b32_dpp v19, v18 quad_perm:[2,3,0,1] row_mask:0xf bank_mask:0xf
	s_waitcnt lgkmcnt(0)
	v_add_f32_e32 v18, v18, v19
	s_nop 1
	v_mov_b32_dpp v19, v18 row_half_mirror row_mask:0xf bank_mask:0xf
	s_waitcnt lgkmcnt(0)
	v_add_f32_e32 v18, v18, v19
	s_nop 1
	v_mov_b32_dpp v19, v18 row_mirror row_mask:0xf bank_mask:0xf
	s_waitcnt lgkmcnt(0)
	v_add_f32_e32 v18, v18, v19
	ds_bpermute_b32 v19, v32, v18
	s_waitcnt lgkmcnt(0)
	v_add_f32_e32 v18, v18, v19
	ds_bpermute_b32 v19, v33, v18
	s_waitcnt lgkmcnt(0)
	v_add_f32_e32 v20, v18, v19
	v_lshl_add_u64 v[18:19], s[4:5], 0, v[2:3]
	v_fmamk_f32 v2, v20, 0x3b000000, v187
	v_cmp_gt_f32_e32 vcc, s28, v2
	v_mul_f32_e32 v3, 0x4b800000, v2
	s_nop 0
	v_cndmask_b32_e32 v2, v2, v3, vcc
	v_rsq_f32_e32 v2, v2
	s_nop 0
	v_mul_f32_e32 v3, 0x45800000, v2
	v_cndmask_b32_e32 v2, v2, v3, vcc
	v_mul_f32_e32 v3, v2, v15
	v_mul_f32_e32 v15, v2, v26
	v_cvt_pk_bf16_f32 v20, v3, v15
	v_mul_f32_e32 v3, v2, v27
	v_mul_f32_e32 v15, v2, v34
	v_cvt_pk_bf16_f32 v21, v3, v15
	v_mul_f32_e32 v3, v2, v23
	v_mul_f32_e32 v15, v2, v22
	v_cvt_pk_bf16_f32 v22, v3, v15
	v_mul_f32_e32 v3, v2, v25
	v_mul_f32_e32 v2, v2, v24
	v_cvt_pk_bf16_f32 v23, v3, v2
	v_lshl_add_u64 v[2:3], v[18:19], 0, v[6:7]
	global_store_dwordx4 v[2:3], v[20:23], off
	v_lshlrev_b64 v[2:3], 9, v[0:1]
	v_mad_i64_i32 v[0:1], s[0:1], v0, s93, v[16:17]
	v_lshl_add_u64 v[0:1], v[0:1], 0, v[168:169]
	v_add_co_u32_e32 v0, vcc, s29, v0
	v_lshl_add_u64 v[20:21], v[10:11], 0, v[2:3]
	v_lshl_add_u64 v[2:3], v[8:9], 0, v[2:3]
	v_addc_co_u32_e32 v1, vcc, 0, v1, vcc
	global_load_dwordx2 v[24:25], v[20:21], off
	global_load_dwordx2 v[22:23], v[2:3], off
	global_load_dwordx2 v[26:27], v[0:1], off offset:3072
	s_nop 0
	global_load_dwordx4 v[0:3], v[4:5], off
	s_waitcnt vmcnt(3)
	v_lshlrev_b32_e32 v20, 16, v25
	s_waitcnt vmcnt(1)
	v_lshlrev_b32_e32 v36, 16, v27
	v_mul_f32_e32 v15, 0x3d372713, v36
	v_lshlrev_b32_e32 v34, 16, v23
	v_and_b32_e32 v35, 0xffff0000, v23
	v_mul_f32_e32 v15, v15, v36
	v_mov_b32_e32 v23, v36
	v_fmac_f32_e32 v23, v15, v23
	v_mul_f32_e32 v15, 0x3f4c422a, v23
	v_add_f32_e32 v15, v15, v15
	v_and_b32_e32 v37, 0xffff0000, v27
	v_mul_f32_e32 v15, 0x3fb8aa3b, v15
	v_and_b32_e32 v21, 0xffff0000, v25
	v_exp_f32_e32 v38, v15
	v_mul_f32_e32 v15, 0x3d372713, v37
	s_waitcnt vmcnt(0)
	v_pk_fma_f32 v[2:3], v[2:3], v[34:35], v[20:21]
	v_mul_f32_e32 v15, v15, v37
	v_mov_b32_e32 v20, v37
	v_fmac_f32_e32 v20, v15, v20
	v_mul_f32_e32 v15, 0x3f4c422a, v20
	v_add_f32_e32 v15, v15, v15
	v_mul_f32_e32 v15, 0x3fb8aa3b, v15
	v_exp_f32_e32 v39, v15
	s_nop 0
	v_pk_add_f32 v[20:21], v[38:39], 1.0 op_sel_hi:[1,0]
	s_nop 0
	v_div_scale_f32 v15, s[0:1], v21, v21, 2.0
	v_rcp_f32_e32 v23, v15
	s_nop 0
	v_fma_f32 v25, -v15, v23, 1.0
	v_fmac_f32_e32 v23, v25, v23
	v_div_scale_f32 v25, vcc, 2.0, v21, 2.0
	v_mul_f32_e32 v27, v25, v23
	v_fma_f32 v34, -v15, v27, v25
	v_fmac_f32_e32 v27, v34, v23
	v_fma_f32 v15, -v15, v27, v25
	v_div_fmas_f32 v15, v15, v23, v27
	v_div_fixup_f32 v21, v15, v21, 2.0
	v_div_scale_f32 v15, s[0:1], v20, v20, 2.0
	v_rcp_f32_e32 v23, v15
	s_nop 0
	v_fma_f32 v25, -v15, v23, 1.0
	v_fmac_f32_e32 v23, v25, v23
	v_div_scale_f32 v25, vcc, 2.0, v20, 2.0
	v_mul_f32_e32 v27, v25, v23
	v_fma_f32 v34, -v15, v27, v25
	v_fmac_f32_e32 v27, v34, v23
	v_fma_f32 v15, -v15, v27, v25
	v_div_fmas_f32 v15, v15, v23, v27
	v_div_fixup_f32 v20, v15, v20, 2.0
	v_pk_add_f32 v[20:21], v[20:21], 1.0 op_sel_hi:[1,0] neg_lo:[1,0] neg_hi:[1,0]
	v_pk_mul_f32 v[34:35], v[36:37], 0.5 op_sel_hi:[1,0]
	v_pk_add_f32 v[20:21], v[20:21], 1.0 op_sel_hi:[1,0]
	v_lshlrev_b32_e32 v36, 16, v22
	v_pk_mul_f32 v[20:21], v[34:35], v[20:21]
	v_lshlrev_b32_e32 v34, 16, v24
	v_and_b32_e32 v35, 0xffff0000, v24
	v_lshlrev_b32_e32 v24, 16, v26
	v_mul_f32_e32 v15, 0x3d372713, v24
	v_and_b32_e32 v37, 0xffff0000, v22
	v_mul_f32_e32 v15, v15, v24
	v_mov_b32_e32 v22, v24
	v_fmac_f32_e32 v22, v15, v22
	v_mul_f32_e32 v15, 0x3f4c422a, v22
	v_add_f32_e32 v15, v15, v15
	v_and_b32_e32 v25, 0xffff0000, v26
	v_mul_f32_e32 v15, 0x3fb8aa3b, v15
	v_exp_f32_e32 v22, v15
	v_mul_f32_e32 v15, 0x3d372713, v25
	v_mul_f32_e32 v15, v15, v25
	v_mov_b32_e32 v23, v25
	v_fmac_f32_e32 v23, v15, v23
	v_mul_f32_e32 v15, 0x3f4c422a, v23
	v_add_f32_e32 v15, v15, v15
	v_mul_f32_e32 v15, 0x3fb8aa3b, v15
	v_exp_f32_e32 v23, v15
	v_pk_fma_f32 v[0:1], v[0:1], v[36:37], v[34:35]
	v_pk_mul_f32 v[24:25], v[24:25], 0.5 op_sel_hi:[1,0]
	v_pk_mul_f32 v[2:3], v[2:3], v[20:21]
	v_pk_add_f32 v[22:23], v[22:23], 1.0 op_sel_hi:[1,0]
	v_pk_mul_f32 v[20:21], v[2:3], v[2:3]
	v_div_scale_f32 v15, s[0:1], v23, v23, 2.0
	v_rcp_f32_e32 v26, v15
	s_nop 0
	v_fma_f32 v27, -v15, v26, 1.0
	v_fmac_f32_e32 v26, v27, v26
	v_div_scale_f32 v27, vcc, 2.0, v23, 2.0
	v_mul_f32_e32 v34, v27, v26
	v_fma_f32 v35, -v15, v34, v27
	v_fmac_f32_e32 v34, v35, v26
	v_fma_f32 v15, -v15, v34, v27
	v_div_fmas_f32 v15, v15, v26, v34
	v_div_fixup_f32 v23, v15, v23, 2.0
	v_div_scale_f32 v15, s[0:1], v22, v22, 2.0
	v_rcp_f32_e32 v26, v15
	s_nop 0
	v_fma_f32 v27, -v15, v26, 1.0
	v_fmac_f32_e32 v26, v27, v26
	v_div_scale_f32 v27, vcc, 2.0, v22, 2.0
	v_mul_f32_e32 v34, v27, v26
	v_fma_f32 v35, -v15, v34, v27
	v_fmac_f32_e32 v34, v35, v26
	v_fma_f32 v15, -v15, v34, v27
	v_div_fmas_f32 v15, v15, v26, v34
	v_div_fixup_f32 v22, v15, v22, 2.0
	v_pk_add_f32 v[22:23], v[22:23], 1.0 op_sel_hi:[1,0] neg_lo:[1,0] neg_hi:[1,0]
	s_nop 0
	v_pk_add_f32 v[22:23], v[22:23], 1.0 op_sel_hi:[1,0]
	s_nop 0
	v_pk_mul_f32 v[22:23], v[24:25], v[22:23]
	s_nop 0
	v_pk_mul_f32 v[0:1], v[0:1], v[22:23]
	s_nop 0
	v_pk_mul_f32 v[22:23], v[0:1], v[0:1]
	s_nop 0
	v_add_f32_e32 v15, v22, v23
	v_add_f32_e32 v15, v20, v15
	v_add_f32_e32 v15, v21, v15
	s_nop 1
	v_mov_b32_dpp v20, v15 quad_perm:[1,0,3,2] row_mask:0xf bank_mask:0xf
	s_waitcnt lgkmcnt(0)
	v_add_f32_e32 v15, v15, v20
	s_nop 1
	v_mov_b32_dpp v20, v15 quad_perm:[2,3,0,1] row_mask:0xf bank_mask:0xf
	s_waitcnt lgkmcnt(0)
	v_add_f32_e32 v15, v15, v20
	s_nop 1
	v_mov_b32_dpp v20, v15 row_half_mirror row_mask:0xf bank_mask:0xf
	s_waitcnt lgkmcnt(0)
	v_add_f32_e32 v15, v15, v20
	s_nop 1
	v_mov_b32_dpp v20, v15 row_mirror row_mask:0xf bank_mask:0xf
	s_waitcnt lgkmcnt(0)
	v_add_f32_e32 v15, v15, v20
	ds_bpermute_b32 v20, v32, v15
	s_waitcnt lgkmcnt(0)
	v_add_f32_e32 v15, v15, v20
	ds_bpermute_b32 v20, v33, v15
	s_waitcnt lgkmcnt(0)
	v_add_f32_e32 v15, v15, v20
	v_fmamk_f32 v15, v15, 0x3b800000, v187
	v_cmp_gt_f32_e32 vcc, s28, v15
	v_mul_f32_e32 v20, 0x4b800000, v15
	s_nop 0
	v_cndmask_b32_e32 v15, v15, v20, vcc
	v_rsq_f32_e32 v15, v15
	s_nop 0
	v_mul_f32_e32 v20, 0x45800000, v15
	v_cndmask_b32_e32 v20, v15, v20, vcc
	v_pk_mul_f32 v[0:1], v[0:1], v[20:21] op_sel_hi:[1,0]
	v_pk_mul_f32 v[2:3], v[2:3], v[20:21] op_sel_hi:[1,0]
	v_cvt_pk_bf16_f32 v0, v0, v1
	v_cvt_pk_bf16_f32 v1, v2, v3
	v_lshl_add_u64 v[2:3], v[18:19], 0, v[168:169]
	global_store_dwordx2 v[2:3], v[0:1], off offset:1536
	v_add_u32_e32 v0, 2, v14
	v_ashrrev_i32_e32 v1, 31, v0
	v_lshlrev_b64 v[18:19], 10, v[0:1]
	v_lshl_add_u64 v[18:19], v[12:13], 0, v[18:19]
	global_load_dwordx4 v[18:21], v[18:19], off
	v_lshlrev_b64 v[2:3], 11, v[0:1]
	s_waitcnt vmcnt(0)
	v_and_b32_e32 v26, 0xffff0000, v18
	v_lshlrev_b32_e32 v15, 16, v18
	v_mul_f32_e32 v24, v26, v26
	v_lshlrev_b32_e32 v27, 16, v19
	v_fmac_f32_e32 v24, v15, v15
	v_and_b32_e32 v34, 0xffff0000, v19
	v_fmac_f32_e32 v24, v27, v27
	v_and_b32_e32 v22, 0xffff0000, v20
	v_lshlrev_b32_e32 v23, 16, v20
	v_fmac_f32_e32 v24, v34, v34
	v_pk_mul_f32 v[18:19], v[22:23], v[22:23]
	v_lshlrev_b32_e32 v25, 16, v21
	v_add_f32_e32 v19, v19, v24
	v_and_b32_e32 v24, 0xffff0000, v21
	v_add_f32_e32 v20, v18, v19
	v_pk_mul_f32 v[18:19], v[24:25], v[24:25]
	s_nop 0
	v_add_f32_e32 v19, v19, v20
	v_add_f32_e32 v18, v18, v19
	s_nop 1
	v_mov_b32_dpp v19, v18 quad_perm:[1,0,3,2] row_mask:0xf bank_mask:0xf
	s_waitcnt lgkmcnt(0)
	v_add_f32_e32 v18, v18, v19
	s_nop 1
	v_mov_b32_dpp v19, v18 quad_perm:[2,3,0,1] row_mask:0xf bank_mask:0xf
	s_waitcnt lgkmcnt(0)
	v_add_f32_e32 v18, v18, v19
	s_nop 1
	v_mov_b32_dpp v19, v18 row_half_mirror row_mask:0xf bank_mask:0xf
	s_waitcnt lgkmcnt(0)
	v_add_f32_e32 v18, v18, v19
	s_nop 1
	v_mov_b32_dpp v19, v18 row_mirror row_mask:0xf bank_mask:0xf
	s_waitcnt lgkmcnt(0)
	v_add_f32_e32 v18, v18, v19
	ds_bpermute_b32 v19, v32, v18
	s_waitcnt lgkmcnt(0)
	v_add_f32_e32 v18, v18, v19
	ds_bpermute_b32 v19, v33, v18
	s_waitcnt lgkmcnt(0)
	v_add_f32_e32 v20, v18, v19
	v_lshl_add_u64 v[18:19], s[4:5], 0, v[2:3]
	v_fmamk_f32 v2, v20, 0x3b000000, v187
	v_cmp_gt_f32_e32 vcc, s28, v2
	v_mul_f32_e32 v3, 0x4b800000, v2
	s_nop 0
	v_cndmask_b32_e32 v2, v2, v3, vcc
	v_rsq_f32_e32 v2, v2
	s_nop 0
	v_mul_f32_e32 v3, 0x45800000, v2
	v_cndmask_b32_e32 v2, v2, v3, vcc
	v_mul_f32_e32 v3, v2, v15
	v_mul_f32_e32 v15, v2, v26
	v_cvt_pk_bf16_f32 v20, v3, v15
	v_mul_f32_e32 v3, v2, v27
	v_mul_f32_e32 v15, v2, v34
	v_cvt_pk_bf16_f32 v21, v3, v15
	v_mul_f32_e32 v3, v2, v23
	v_mul_f32_e32 v15, v2, v22
	v_cvt_pk_bf16_f32 v22, v3, v15
	v_mul_f32_e32 v3, v2, v25
	v_mul_f32_e32 v2, v2, v24
	v_cvt_pk_bf16_f32 v23, v3, v2
	v_lshl_add_u64 v[2:3], v[18:19], 0, v[6:7]
	global_store_dwordx4 v[2:3], v[20:23], off
	v_lshlrev_b64 v[2:3], 9, v[0:1]
	v_mad_i64_i32 v[0:1], s[0:1], v0, s93, v[16:17]
	v_lshl_add_u64 v[0:1], v[0:1], 0, v[168:169]
	v_add_co_u32_e32 v0, vcc, s29, v0
	v_lshl_add_u64 v[20:21], v[10:11], 0, v[2:3]
	v_lshl_add_u64 v[2:3], v[8:9], 0, v[2:3]
	v_addc_co_u32_e32 v1, vcc, 0, v1, vcc
	global_load_dwordx2 v[24:25], v[20:21], off
	global_load_dwordx2 v[22:23], v[2:3], off
	global_load_dwordx2 v[26:27], v[0:1], off offset:3072
	s_nop 0
	global_load_dwordx4 v[0:3], v[4:5], off
	s_waitcnt vmcnt(3)
	v_lshlrev_b32_e32 v20, 16, v25
	s_waitcnt vmcnt(1)
	v_lshlrev_b32_e32 v36, 16, v27
	v_mul_f32_e32 v15, 0x3d372713, v36
	v_lshlrev_b32_e32 v34, 16, v23
	v_and_b32_e32 v35, 0xffff0000, v23
	v_mul_f32_e32 v15, v15, v36
	v_mov_b32_e32 v23, v36
	v_fmac_f32_e32 v23, v15, v23
	v_mul_f32_e32 v15, 0x3f4c422a, v23
	v_add_f32_e32 v15, v15, v15
	v_and_b32_e32 v37, 0xffff0000, v27
	v_mul_f32_e32 v15, 0x3fb8aa3b, v15
	v_and_b32_e32 v21, 0xffff0000, v25
	v_exp_f32_e32 v38, v15
	v_mul_f32_e32 v15, 0x3d372713, v37
	s_waitcnt vmcnt(0)
	v_pk_fma_f32 v[2:3], v[2:3], v[34:35], v[20:21]
	v_mul_f32_e32 v15, v15, v37
	v_mov_b32_e32 v20, v37
	v_fmac_f32_e32 v20, v15, v20
	v_mul_f32_e32 v15, 0x3f4c422a, v20
	v_add_f32_e32 v15, v15, v15
	v_mul_f32_e32 v15, 0x3fb8aa3b, v15
	v_exp_f32_e32 v39, v15
	s_nop 0
	v_pk_add_f32 v[20:21], v[38:39], 1.0 op_sel_hi:[1,0]
	s_nop 0
	v_div_scale_f32 v15, s[0:1], v21, v21, 2.0
	v_rcp_f32_e32 v23, v15
	s_nop 0
	v_fma_f32 v25, -v15, v23, 1.0
	v_fmac_f32_e32 v23, v25, v23
	v_div_scale_f32 v25, vcc, 2.0, v21, 2.0
	v_mul_f32_e32 v27, v25, v23
	v_fma_f32 v34, -v15, v27, v25
	v_fmac_f32_e32 v27, v34, v23
	v_fma_f32 v15, -v15, v27, v25
	v_div_fmas_f32 v15, v15, v23, v27
	v_div_fixup_f32 v21, v15, v21, 2.0
	v_div_scale_f32 v15, s[0:1], v20, v20, 2.0
	v_rcp_f32_e32 v23, v15
	s_nop 0
	v_fma_f32 v25, -v15, v23, 1.0
	v_fmac_f32_e32 v23, v25, v23
	v_div_scale_f32 v25, vcc, 2.0, v20, 2.0
	v_mul_f32_e32 v27, v25, v23
	v_fma_f32 v34, -v15, v27, v25
	v_fmac_f32_e32 v27, v34, v23
	v_fma_f32 v15, -v15, v27, v25
	v_div_fmas_f32 v15, v15, v23, v27
	v_div_fixup_f32 v20, v15, v20, 2.0
	v_pk_add_f32 v[20:21], v[20:21], 1.0 op_sel_hi:[1,0] neg_lo:[1,0] neg_hi:[1,0]
	v_pk_mul_f32 v[34:35], v[36:37], 0.5 op_sel_hi:[1,0]
	v_pk_add_f32 v[20:21], v[20:21], 1.0 op_sel_hi:[1,0]
	v_lshlrev_b32_e32 v36, 16, v22
	v_pk_mul_f32 v[20:21], v[34:35], v[20:21]
	v_lshlrev_b32_e32 v34, 16, v24
	v_and_b32_e32 v35, 0xffff0000, v24
	v_lshlrev_b32_e32 v24, 16, v26
	v_mul_f32_e32 v15, 0x3d372713, v24
	v_and_b32_e32 v37, 0xffff0000, v22
	v_mul_f32_e32 v15, v15, v24
	v_mov_b32_e32 v22, v24
	v_fmac_f32_e32 v22, v15, v22
	v_mul_f32_e32 v15, 0x3f4c422a, v22
	v_add_f32_e32 v15, v15, v15
	v_and_b32_e32 v25, 0xffff0000, v26
	v_mul_f32_e32 v15, 0x3fb8aa3b, v15
	v_exp_f32_e32 v22, v15
	v_mul_f32_e32 v15, 0x3d372713, v25
	v_mul_f32_e32 v15, v15, v25
	v_mov_b32_e32 v23, v25
	v_fmac_f32_e32 v23, v15, v23
	v_mul_f32_e32 v15, 0x3f4c422a, v23
	v_add_f32_e32 v15, v15, v15
	v_mul_f32_e32 v15, 0x3fb8aa3b, v15
	v_exp_f32_e32 v23, v15
	v_pk_fma_f32 v[0:1], v[0:1], v[36:37], v[34:35]
	v_pk_mul_f32 v[24:25], v[24:25], 0.5 op_sel_hi:[1,0]
	v_pk_mul_f32 v[2:3], v[2:3], v[20:21]
	v_pk_add_f32 v[22:23], v[22:23], 1.0 op_sel_hi:[1,0]
	v_pk_mul_f32 v[20:21], v[2:3], v[2:3]
	v_div_scale_f32 v15, s[0:1], v23, v23, 2.0
	v_rcp_f32_e32 v26, v15
	s_nop 0
	v_fma_f32 v27, -v15, v26, 1.0
	v_fmac_f32_e32 v26, v27, v26
	v_div_scale_f32 v27, vcc, 2.0, v23, 2.0
	v_mul_f32_e32 v34, v27, v26
	v_fma_f32 v35, -v15, v34, v27
	v_fmac_f32_e32 v34, v35, v26
	v_fma_f32 v15, -v15, v34, v27
	v_div_fmas_f32 v15, v15, v26, v34
	v_div_fixup_f32 v23, v15, v23, 2.0
	v_div_scale_f32 v15, s[0:1], v22, v22, 2.0
	v_rcp_f32_e32 v26, v15
	s_nop 0
	v_fma_f32 v27, -v15, v26, 1.0
	v_fmac_f32_e32 v26, v27, v26
	v_div_scale_f32 v27, vcc, 2.0, v22, 2.0
	v_mul_f32_e32 v34, v27, v26
	v_fma_f32 v35, -v15, v34, v27
	v_fmac_f32_e32 v34, v35, v26
	v_fma_f32 v15, -v15, v34, v27
	v_div_fmas_f32 v15, v15, v26, v34
	v_div_fixup_f32 v22, v15, v22, 2.0
	v_pk_add_f32 v[22:23], v[22:23], 1.0 op_sel_hi:[1,0] neg_lo:[1,0] neg_hi:[1,0]
	s_nop 0
	v_pk_add_f32 v[22:23], v[22:23], 1.0 op_sel_hi:[1,0]
	s_nop 0
	v_pk_mul_f32 v[22:23], v[24:25], v[22:23]
	s_nop 0
	v_pk_mul_f32 v[0:1], v[0:1], v[22:23]
	s_nop 0
	v_pk_mul_f32 v[22:23], v[0:1], v[0:1]
	s_nop 0
	v_add_f32_e32 v15, v22, v23
	v_add_f32_e32 v15, v20, v15
	v_add_f32_e32 v15, v21, v15
	s_nop 1
	v_mov_b32_dpp v20, v15 quad_perm:[1,0,3,2] row_mask:0xf bank_mask:0xf
	s_waitcnt lgkmcnt(0)
	v_add_f32_e32 v15, v15, v20
	s_nop 1
	v_mov_b32_dpp v20, v15 quad_perm:[2,3,0,1] row_mask:0xf bank_mask:0xf
	s_waitcnt lgkmcnt(0)
	v_add_f32_e32 v15, v15, v20
	s_nop 1
	v_mov_b32_dpp v20, v15 row_half_mirror row_mask:0xf bank_mask:0xf
	s_waitcnt lgkmcnt(0)
	v_add_f32_e32 v15, v15, v20
	s_nop 1
	v_mov_b32_dpp v20, v15 row_mirror row_mask:0xf bank_mask:0xf
	s_waitcnt lgkmcnt(0)
	v_add_f32_e32 v15, v15, v20
	ds_bpermute_b32 v20, v32, v15
	s_waitcnt lgkmcnt(0)
	v_add_f32_e32 v15, v15, v20
	ds_bpermute_b32 v20, v33, v15
	s_waitcnt lgkmcnt(0)
	v_add_f32_e32 v15, v15, v20
	v_fmamk_f32 v15, v15, 0x3b800000, v187
	v_cmp_gt_f32_e32 vcc, s28, v15
	v_mul_f32_e32 v20, 0x4b800000, v15
	s_nop 0
	v_cndmask_b32_e32 v15, v15, v20, vcc
	v_rsq_f32_e32 v15, v15
	s_nop 0
	v_mul_f32_e32 v20, 0x45800000, v15
	v_cndmask_b32_e32 v20, v15, v20, vcc
	v_pk_mul_f32 v[0:1], v[0:1], v[20:21] op_sel_hi:[1,0]
	v_pk_mul_f32 v[2:3], v[2:3], v[20:21] op_sel_hi:[1,0]
	v_cvt_pk_bf16_f32 v0, v0, v1
	v_cvt_pk_bf16_f32 v1, v2, v3
	v_lshl_add_u64 v[2:3], v[18:19], 0, v[168:169]
	global_store_dwordx2 v[2:3], v[0:1], off offset:1536
	v_add_u32_e32 v0, 3, v14
	v_ashrrev_i32_e32 v1, 31, v0
	v_lshlrev_b64 v[14:15], 10, v[0:1]
	v_lshl_add_u64 v[12:13], v[12:13], 0, v[14:15]
	global_load_dwordx4 v[12:15], v[12:13], off
	v_lshlrev_b64 v[2:3], 11, v[0:1]
	s_waitcnt vmcnt(0)
	v_and_b32_e32 v19, 0xffff0000, v12
	v_lshlrev_b32_e32 v18, 16, v12
	v_mul_f32_e32 v24, v19, v19
	v_lshlrev_b32_e32 v22, 16, v13
	v_fmac_f32_e32 v24, v18, v18
	v_and_b32_e32 v23, 0xffff0000, v13
	v_fmac_f32_e32 v24, v22, v22
	v_and_b32_e32 v20, 0xffff0000, v14
	v_lshlrev_b32_e32 v21, 16, v14
	v_fmac_f32_e32 v24, v23, v23
	v_pk_mul_f32 v[12:13], v[20:21], v[20:21]
	v_and_b32_e32 v14, 0xffff0000, v15
	v_add_f32_e32 v13, v13, v24
	v_lshlrev_b32_e32 v15, 16, v15
	v_add_f32_e32 v24, v12, v13
	v_pk_mul_f32 v[12:13], v[14:15], v[14:15]
	s_nop 0
	v_add_f32_e32 v13, v13, v24
	v_add_f32_e32 v12, v12, v13
	s_nop 1
	v_mov_b32_dpp v13, v12 quad_perm:[1,0,3,2] row_mask:0xf bank_mask:0xf
	s_waitcnt lgkmcnt(0)
	v_add_f32_e32 v12, v12, v13
	s_nop 1
	v_mov_b32_dpp v13, v12 quad_perm:[2,3,0,1] row_mask:0xf bank_mask:0xf
	s_waitcnt lgkmcnt(0)
	v_add_f32_e32 v12, v12, v13
	s_nop 1
	v_mov_b32_dpp v13, v12 row_half_mirror row_mask:0xf bank_mask:0xf
	s_waitcnt lgkmcnt(0)
	v_add_f32_e32 v12, v12, v13
	s_nop 1
	v_mov_b32_dpp v13, v12 row_mirror row_mask:0xf bank_mask:0xf
	s_waitcnt lgkmcnt(0)
	v_add_f32_e32 v12, v12, v13
	ds_bpermute_b32 v13, v32, v12
	s_waitcnt lgkmcnt(0)
	v_add_f32_e32 v12, v12, v13
	ds_bpermute_b32 v13, v33, v12
	s_waitcnt lgkmcnt(0)
	v_add_f32_e32 v24, v12, v13
	v_lshl_add_u64 v[12:13], s[4:5], 0, v[2:3]
	v_fmamk_f32 v2, v24, 0x3b000000, v187
	v_cmp_gt_f32_e32 vcc, s28, v2
	v_mul_f32_e32 v3, 0x4b800000, v2
	s_nop 0
	v_cndmask_b32_e32 v2, v2, v3, vcc
	v_rsq_f32_e32 v2, v2
	s_nop 0
	v_mul_f32_e32 v3, 0x45800000, v2
	v_cndmask_b32_e32 v2, v2, v3, vcc
	v_mul_f32_e32 v3, v2, v18
	v_mul_f32_e32 v18, v2, v19
	v_cvt_pk_bf16_f32 v18, v3, v18
	v_mul_f32_e32 v3, v2, v22
	v_mul_f32_e32 v19, v2, v23
	v_cvt_pk_bf16_f32 v19, v3, v19
	v_mul_f32_e32 v3, v2, v21
	v_mul_f32_e32 v20, v2, v20
	v_cvt_pk_bf16_f32 v20, v3, v20
	v_mul_f32_e32 v3, v2, v15
	v_mul_f32_e32 v2, v2, v14
	v_cvt_pk_bf16_f32 v21, v3, v2
	v_lshl_add_u64 v[2:3], v[12:13], 0, v[6:7]
	global_store_dwordx4 v[2:3], v[18:21], off
	v_lshlrev_b64 v[2:3], 9, v[0:1]
	v_mad_i64_i32 v[0:1], s[0:1], v0, s93, v[16:17]
	v_lshl_add_u64 v[0:1], v[0:1], 0, v[168:169]
	v_lshl_add_u64 v[6:7], v[10:11], 0, v[2:3]
	v_lshl_add_u64 v[2:3], v[8:9], 0, v[2:3]
	v_add_co_u32_e32 v0, vcc, s29, v0
	global_load_dwordx2 v[10:11], v[6:7], off
	s_nop 0
	v_addc_co_u32_e32 v1, vcc, 0, v1, vcc
	global_load_dwordx2 v[6:7], v[2:3], off
	global_load_dwordx2 v[14:15], v[0:1], off offset:3072
	s_nop 0
	global_load_dwordx4 v[0:3], v[4:5], off
	s_waitcnt vmcnt(3)
	v_lshlrev_b32_e32 v4, 16, v11
	v_and_b32_e32 v5, 0xffff0000, v11
	s_waitcnt vmcnt(2)
	v_lshlrev_b32_e32 v8, 16, v7
	v_and_b32_e32 v9, 0xffff0000, v7
	s_waitcnt vmcnt(1)
	v_lshlrev_b32_e32 v16, 16, v15
	v_and_b32_e32 v17, 0xffff0000, v15
	v_mul_f32_e32 v7, 0x3d372713, v16
	s_waitcnt vmcnt(0)
	v_pk_fma_f32 v[2:3], v[2:3], v[8:9], v[4:5]
	v_mul_f32_e32 v4, 0x3d372713, v17
	v_mul_f32_e32 v7, v7, v16
	v_mov_b32_e32 v11, v16
	v_mul_f32_e32 v4, v4, v17
	v_mov_b32_e32 v5, v17
	v_fmac_f32_e32 v11, v7, v11
	v_fmac_f32_e32 v5, v4, v5
	v_mul_f32_e32 v7, 0x3f4c422a, v11
	v_mul_f32_e32 v4, 0x3f4c422a, v5
	v_add_f32_e32 v7, v7, v7
	v_add_f32_e32 v4, v4, v4
	v_mul_f32_e32 v7, 0x3fb8aa3b, v7
	v_mul_f32_e32 v4, 0x3fb8aa3b, v4
	v_exp_f32_e32 v18, v7
	v_exp_f32_e32 v19, v4
	s_nop 0
	v_pk_add_f32 v[4:5], v[18:19], 1.0 op_sel_hi:[1,0]
	s_nop 0
	v_div_scale_f32 v7, s[0:1], v5, v5, 2.0
	v_rcp_f32_e32 v8, v7
	s_nop 0
	v_fma_f32 v9, -v7, v8, 1.0
	v_fmac_f32_e32 v8, v9, v8
	v_div_scale_f32 v9, vcc, 2.0, v5, 2.0
	v_mul_f32_e32 v11, v9, v8
	v_fma_f32 v15, -v7, v11, v9
	v_fmac_f32_e32 v11, v15, v8
	v_fma_f32 v7, -v7, v11, v9
	v_div_fmas_f32 v7, v7, v8, v11
	v_div_fixup_f32 v5, v7, v5, 2.0
	v_div_scale_f32 v7, s[0:1], v4, v4, 2.0
	v_rcp_f32_e32 v8, v7
	s_nop 0
	v_fma_f32 v9, -v7, v8, 1.0
	v_fmac_f32_e32 v8, v9, v8
	v_div_scale_f32 v9, vcc, 2.0, v4, 2.0
	v_mul_f32_e32 v11, v9, v8
	v_fma_f32 v15, -v7, v11, v9
	v_fmac_f32_e32 v11, v15, v8
	v_fma_f32 v7, -v7, v11, v9
	v_div_fmas_f32 v7, v7, v8, v11
	v_div_fixup_f32 v4, v7, v4, 2.0
	v_pk_add_f32 v[4:5], v[4:5], 1.0 op_sel_hi:[1,0] neg_lo:[1,0] neg_hi:[1,0]
	v_pk_mul_f32 v[8:9], v[16:17], 0.5 op_sel_hi:[1,0]
	v_pk_add_f32 v[4:5], v[4:5], 1.0 op_sel_hi:[1,0]
	v_lshlrev_b32_e32 v16, 16, v10
	v_pk_mul_f32 v[4:5], v[8:9], v[4:5]
	v_lshlrev_b32_e32 v8, 16, v14
	v_and_b32_e32 v17, 0xffff0000, v10
	v_lshlrev_b32_e32 v10, 16, v6
	v_and_b32_e32 v11, 0xffff0000, v6
	v_mul_f32_e32 v6, 0x3d372713, v8
	v_mul_f32_e32 v6, v6, v8
	v_mov_b32_e32 v7, v8
	v_and_b32_e32 v9, 0xffff0000, v14
	v_fmac_f32_e32 v7, v6, v7
	v_mul_f32_e32 v6, 0x3f4c422a, v7
	v_mul_f32_e32 v7, 0x3d372713, v9
	v_pk_fma_f32 v[0:1], v[0:1], v[10:11], v[16:17]
	v_mul_f32_e32 v7, v7, v9
	v_mov_b32_e32 v10, v9
	v_fmac_f32_e32 v10, v7, v10
	v_mul_f32_e32 v7, 0x3f4c422a, v10
	v_add_f32_e32 v6, v6, v6
	v_add_f32_e32 v7, v7, v7
	v_mul_f32_e32 v6, 0x3fb8aa3b, v6
	v_mul_f32_e32 v7, 0x3fb8aa3b, v7
	v_exp_f32_e32 v6, v6
	v_exp_f32_e32 v7, v7
	v_pk_mul_f32 v[8:9], v[8:9], 0.5 op_sel_hi:[1,0]
	v_pk_mul_f32 v[2:3], v[2:3], v[4:5]
	v_pk_add_f32 v[6:7], v[6:7], 1.0 op_sel_hi:[1,0]
	s_nop 0
	v_div_scale_f32 v10, s[0:1], v7, v7, 2.0
	v_rcp_f32_e32 v11, v10
	v_pk_mul_f32 v[4:5], v[2:3], v[2:3]
	v_fma_f32 v14, -v10, v11, 1.0
	v_fmac_f32_e32 v11, v14, v11
	v_div_scale_f32 v14, vcc, 2.0, v7, 2.0
	v_mul_f32_e32 v15, v14, v11
	v_fma_f32 v16, -v10, v15, v14
	v_fmac_f32_e32 v15, v16, v11
	v_fma_f32 v10, -v10, v15, v14
	v_div_fmas_f32 v10, v10, v11, v15
	v_div_fixup_f32 v7, v10, v7, 2.0
	v_div_scale_f32 v10, s[0:1], v6, v6, 2.0
	v_rcp_f32_e32 v11, v10
	s_nop 0
	v_fma_f32 v14, -v10, v11, 1.0
	v_fmac_f32_e32 v11, v14, v11
	v_div_scale_f32 v14, vcc, 2.0, v6, 2.0
	v_mul_f32_e32 v15, v14, v11
	v_fma_f32 v16, -v10, v15, v14
	v_fmac_f32_e32 v15, v16, v11
	v_fma_f32 v10, -v10, v15, v14
	v_div_fmas_f32 v10, v10, v11, v15
	v_div_fixup_f32 v6, v10, v6, 2.0
	v_pk_add_f32 v[6:7], v[6:7], 1.0 op_sel_hi:[1,0] neg_lo:[1,0] neg_hi:[1,0]
	s_nop 0
	v_pk_add_f32 v[6:7], v[6:7], 1.0 op_sel_hi:[1,0]
	s_nop 0
	v_pk_mul_f32 v[6:7], v[8:9], v[6:7]
	s_nop 0
	v_pk_mul_f32 v[0:1], v[0:1], v[6:7]
	s_nop 0
	v_pk_mul_f32 v[6:7], v[0:1], v[0:1]
	s_nop 0
	v_add_f32_e32 v6, v6, v7
	v_add_f32_e32 v4, v4, v6
	v_add_f32_e32 v4, v5, v4
	s_nop 1
	v_mov_b32_dpp v5, v4 quad_perm:[1,0,3,2] row_mask:0xf bank_mask:0xf
	s_waitcnt lgkmcnt(0)
	v_add_f32_e32 v4, v4, v5
	s_nop 1
	v_mov_b32_dpp v5, v4 quad_perm:[2,3,0,1] row_mask:0xf bank_mask:0xf
	s_waitcnt lgkmcnt(0)
	v_add_f32_e32 v4, v4, v5
	s_nop 1
	v_mov_b32_dpp v5, v4 row_half_mirror row_mask:0xf bank_mask:0xf
	s_waitcnt lgkmcnt(0)
	v_add_f32_e32 v4, v4, v5
	s_nop 1
	v_mov_b32_dpp v5, v4 row_mirror row_mask:0xf bank_mask:0xf
	s_waitcnt lgkmcnt(0)
	v_add_f32_e32 v4, v4, v5
	ds_bpermute_b32 v5, v32, v4
	s_waitcnt lgkmcnt(0)
	v_add_f32_e32 v4, v4, v5
	ds_bpermute_b32 v5, v33, v4
	s_waitcnt lgkmcnt(0)
	v_add_f32_e32 v4, v4, v5
	v_fmamk_f32 v4, v4, 0x3b800000, v187
	v_cmp_gt_f32_e32 vcc, s28, v4
	v_mul_f32_e32 v5, 0x4b800000, v4
	s_nop 0
	v_cndmask_b32_e32 v4, v4, v5, vcc
	v_rsq_f32_e32 v4, v4
	s_nop 0
	v_mul_f32_e32 v5, 0x45800000, v4
	v_cndmask_b32_e32 v4, v4, v5, vcc
	v_pk_mul_f32 v[0:1], v[0:1], v[4:5] op_sel_hi:[1,0]
	v_pk_mul_f32 v[2:3], v[2:3], v[4:5] op_sel_hi:[1,0]
	v_cvt_pk_bf16_f32 v0, v0, v1
	v_cvt_pk_bf16_f32 v1, v2, v3
	v_lshl_add_u64 v[2:3], v[12:13], 0, v[168:169]
	global_store_dwordx2 v[2:3], v[0:1], off offset:1536
	s_cbranch_execnz .LBB0_803
